# LRU scan: per-thread scan state (32 p, 32 h) kept in registers instead of written back to LDS and re-read; only y is written for the cooperative store
# speedup vs baseline: 1.0004x; 1.0004x over previous
; __global__ void __launch_bounds__(NTHR, 2) fwd(Args args) {
;     ...
;                         float p = 1.f, h = 0.f;
; #pragma unroll 8
;                         for (int i = 0; i < 32; ++i) { const int r = dir == 0 ? 32 * sg + i : 255 - (32 * sg + i); const float a = Al[r * 64 + ch], bb = Bl[r * 64 + ch]; p *= a; h = a * h + bb; Al[r * 64 + ch] = p; Bl[r * 64 + ch] = h; }
;                         seg[(sg * 64 + ch) * 2] = p; seg[(sg * 64 + ch) * 2 + 1] = h;
.LBB0_1440:
	v_lshlrev_b32_e32 v88, 2, v80
	v_add_u32_e32 v6, 7, v84
	v_add_u32_e32 v7, 0, v81
	v_cndmask_b32_e64 v6, v6, v7, s[18:19]
	v_lshl_or_b32 v6, v6, 8, v88
	v_add_u32_e32 v206, s41, v6
	ds_read_b32 v96, v6
	ds_read_b32 v174, v206
	v_add_u32_e32 v6, 6, v84
	v_add_u32_e32 v7, 1, v81
	v_cndmask_b32_e64 v6, v6, v7, s[18:19]
	v_lshl_or_b32 v6, v6, 8, v88
	v_add_u32_e32 v207, s41, v6
	ds_read_b32 v97, v6
	ds_read_b32 v175, v207
	v_add_u32_e32 v6, 5, v84
	v_add_u32_e32 v7, 2, v81
	v_cndmask_b32_e64 v6, v6, v7, s[18:19]
	v_lshl_or_b32 v6, v6, 8, v88
	v_add_u32_e32 v208, s41, v6
	ds_read_b32 v98, v6
	ds_read_b32 v176, v208
	v_add_u32_e32 v6, 4, v84
	v_add_u32_e32 v7, 3, v81
	v_cndmask_b32_e64 v6, v6, v7, s[18:19]
	v_lshl_or_b32 v6, v6, 8, v88
	v_add_u32_e32 v209, s41, v6
	ds_read_b32 v99, v6
	ds_read_b32 v177, v209
	v_add_u32_e32 v6, 3, v84
	v_add_u32_e32 v7, 4, v81
	v_cndmask_b32_e64 v6, v6, v7, s[18:19]
	v_lshl_or_b32 v6, v6, 8, v88
	v_add_u32_e32 v210, s41, v6
	ds_read_b32 v100, v6
	ds_read_b32 v178, v210
	v_add_u32_e32 v6, 2, v84
	v_add_u32_e32 v7, 5, v81
	v_cndmask_b32_e64 v6, v6, v7, s[18:19]
	v_lshl_or_b32 v6, v6, 8, v88
	v_add_u32_e32 v211, s41, v6
	ds_read_b32 v101, v6
	ds_read_b32 v179, v211
	v_add_u32_e32 v6, 1, v84
	v_add_u32_e32 v7, 6, v81
	v_cndmask_b32_e64 v6, v6, v7, s[18:19]
	v_lshl_or_b32 v6, v6, 8, v88
	v_add_u32_e32 v212, s41, v6
	ds_read_b32 v102, v6
	ds_read_b32 v180, v212
	v_add_u32_e32 v6, 0, v84
	v_add_u32_e32 v7, 7, v81
	v_cndmask_b32_e64 v6, v6, v7, s[18:19]
	v_lshl_or_b32 v6, v6, 8, v88
	v_add_u32_e32 v213, s41, v6
	ds_read_b32 v103, v6
	ds_read_b32 v181, v213
	v_add_u32_e32 v6, -1, v84
	v_add_u32_e32 v7, 8, v81
	v_cndmask_b32_e64 v6, v6, v7, s[18:19]
	v_lshl_or_b32 v6, v6, 8, v88
	v_add_u32_e32 v214, s41, v6
	ds_read_b32 v104, v6
	ds_read_b32 v182, v214
	v_add_u32_e32 v6, -2, v84
	v_add_u32_e32 v7, 9, v81
	v_cndmask_b32_e64 v6, v6, v7, s[18:19]
	v_lshl_or_b32 v6, v6, 8, v88
	v_add_u32_e32 v215, s41, v6
	ds_read_b32 v105, v6
	ds_read_b32 v183, v215
	v_add_u32_e32 v6, -3, v84
	v_add_u32_e32 v7, 10, v81
	v_cndmask_b32_e64 v6, v6, v7, s[18:19]
	v_lshl_or_b32 v6, v6, 8, v88
	v_add_u32_e32 v216, s41, v6
	ds_read_b32 v106, v6
	ds_read_b32 v184, v216
	v_add_u32_e32 v6, -4, v84
	v_add_u32_e32 v7, 11, v81
	v_cndmask_b32_e64 v6, v6, v7, s[18:19]
	v_lshl_or_b32 v6, v6, 8, v88
	v_add_u32_e32 v217, s41, v6
	ds_read_b32 v107, v6
	ds_read_b32 v185, v217
	v_add_u32_e32 v6, -5, v84
	v_add_u32_e32 v7, 12, v81
	v_cndmask_b32_e64 v6, v6, v7, s[18:19]
	v_lshl_or_b32 v6, v6, 8, v88
	v_add_u32_e32 v218, s41, v6
	ds_read_b32 v108, v6
	ds_read_b32 v186, v218
	v_add_u32_e32 v6, -6, v84
	v_add_u32_e32 v7, 13, v81
	v_cndmask_b32_e64 v6, v6, v7, s[18:19]
	v_lshl_or_b32 v6, v6, 8, v88
	v_add_u32_e32 v219, s41, v6
	ds_read_b32 v109, v6
	ds_read_b32 v187, v219
	v_add_u32_e32 v6, -7, v84
	v_add_u32_e32 v7, 14, v81
	v_cndmask_b32_e64 v6, v6, v7, s[18:19]
	v_lshl_or_b32 v6, v6, 8, v88
	v_add_u32_e32 v220, s41, v6
	ds_read_b32 v110, v6
	ds_read_b32 v188, v220
	v_add_u32_e32 v6, -8, v84
	v_add_u32_e32 v7, 15, v81
	v_cndmask_b32_e64 v6, v6, v7, s[18:19]
	v_lshl_or_b32 v6, v6, 8, v88
	v_add_u32_e32 v221, s41, v6
	ds_read_b32 v111, v6
	ds_read_b32 v189, v221
	s_waitcnt lgkmcnt(15)
	v_mul_f32_e32 v142, v2, v96
	v_fmac_f32_e32 v174, v3, v96
	v_mul_f32_e32 v143, v142, v97
	v_fmac_f32_e32 v175, v174, v97
	v_mul_f32_e32 v144, v143, v98
	v_fmac_f32_e32 v176, v175, v98
	v_mul_f32_e32 v145, v144, v99
	v_fmac_f32_e32 v177, v176, v99
	v_mul_f32_e32 v146, v145, v100
	v_fmac_f32_e32 v178, v177, v100
	v_mul_f32_e32 v147, v146, v101
	v_fmac_f32_e32 v179, v178, v101
	v_mul_f32_e32 v148, v147, v102
	v_fmac_f32_e32 v180, v179, v102
	v_mul_f32_e32 v149, v148, v103
	v_fmac_f32_e32 v181, v180, v103
	v_add_u32_e32 v6, -9, v84
	v_add_u32_e32 v7, 16, v81
	v_cndmask_b32_e64 v6, v6, v7, s[18:19]
	v_lshl_or_b32 v6, v6, 8, v88
	v_add_u32_e32 v222, s41, v6
	ds_read_b32 v112, v6
	ds_read_b32 v190, v222
	v_add_u32_e32 v6, -10, v84
	v_add_u32_e32 v7, 17, v81
	v_cndmask_b32_e64 v6, v6, v7, s[18:19]
	v_lshl_or_b32 v6, v6, 8, v88
	v_add_u32_e32 v223, s41, v6
	ds_read_b32 v113, v6
	ds_read_b32 v191, v223
	v_add_u32_e32 v6, -11, v84
	v_add_u32_e32 v7, 18, v81
	v_cndmask_b32_e64 v6, v6, v7, s[18:19]
	v_lshl_or_b32 v6, v6, 8, v88
	v_add_u32_e32 v224, s41, v6
	ds_read_b32 v114, v6
	ds_read_b32 v192, v224
	v_add_u32_e32 v6, -12, v84
	v_add_u32_e32 v7, 19, v81
	v_cndmask_b32_e64 v6, v6, v7, s[18:19]
	v_lshl_or_b32 v6, v6, 8, v88
	v_add_u32_e32 v225, s41, v6
	ds_read_b32 v115, v6
	ds_read_b32 v193, v225
	v_add_u32_e32 v6, -13, v84
	v_add_u32_e32 v7, 20, v81
	v_cndmask_b32_e64 v6, v6, v7, s[18:19]
	v_lshl_or_b32 v6, v6, 8, v88
	v_add_u32_e32 v226, s41, v6
	ds_read_b32 v116, v6
	ds_read_b32 v194, v226
	v_add_u32_e32 v6, -14, v84
	v_add_u32_e32 v7, 21, v81
	v_cndmask_b32_e64 v6, v6, v7, s[18:19]
	v_lshl_or_b32 v6, v6, 8, v88
	v_add_u32_e32 v227, s41, v6
	ds_read_b32 v117, v6
	ds_read_b32 v195, v227
	v_add_u32_e32 v6, -15, v84
	v_add_u32_e32 v7, 22, v81
	v_cndmask_b32_e64 v6, v6, v7, s[18:19]
	v_lshl_or_b32 v6, v6, 8, v88
	v_add_u32_e32 v228, s41, v6
	ds_read_b32 v118, v6
	ds_read_b32 v196, v228
	v_add_u32_e32 v6, -16, v84
	v_add_u32_e32 v7, 23, v81
	v_cndmask_b32_e64 v6, v6, v7, s[18:19]
	v_lshl_or_b32 v6, v6, 8, v88
	v_add_u32_e32 v229, s41, v6
	ds_read_b32 v119, v6
	ds_read_b32 v197, v229
	s_waitcnt lgkmcnt(15)
; __global__ void __launch_bounds__(NTHR, 2) fwd(Args args) {
;     ...
;                         for (int i = 0; i < 32; ++i) { const int r = dir == 0 ? 32 * sg + i : 255 - (32 * sg + i); const float a = Al[r * 64 + ch], bb = Bl[r * 64 + ch]; p *= a; h = a * h + bb; Al[r * 64 + ch] = p; Bl[r * 64 + ch] = h; }
;                         seg[(sg * 64 + ch) * 2] = p; seg[(sg * 64 + ch) * 2 + 1] = h;
;                         __syncthreads();
;                         float st = hcar, pt = 1.f, ht = 0.f;
; #pragma unroll
;                         for (int k = 0; k < 8; ++k) { const float sp_ = seg[(k * 64 + ch) * 2], sh_ = seg[(k * 64 + ch) * 2 + 1]; if (k < sg) st = sp_ * st + sh_; ht = sp_ * ht + sh_; pt *= sp_; }
	v_mul_f32_e32 v150, v149, v104
	v_fmac_f32_e32 v182, v181, v104
	v_mul_f32_e32 v151, v150, v105
	v_fmac_f32_e32 v183, v182, v105
	v_mul_f32_e32 v152, v151, v106
	v_fmac_f32_e32 v184, v183, v106
	v_mul_f32_e32 v153, v152, v107
	v_fmac_f32_e32 v185, v184, v107
	v_mul_f32_e32 v154, v153, v108
	v_fmac_f32_e32 v186, v185, v108
	v_mul_f32_e32 v155, v154, v109
	v_fmac_f32_e32 v187, v186, v109
	v_mul_f32_e32 v156, v155, v110
	v_fmac_f32_e32 v188, v187, v110
	v_mul_f32_e32 v157, v156, v111
	v_fmac_f32_e32 v189, v188, v111
	v_add_u32_e32 v6, 0xffffffef, v84
	v_add_u32_e32 v7, 24, v81
	v_cndmask_b32_e64 v6, v6, v7, s[18:19]
	v_lshl_or_b32 v6, v6, 8, v88
	v_add_u32_e32 v230, s41, v6
	ds_read_b32 v120, v6
	ds_read_b32 v198, v230
	v_add_u32_e32 v6, 0xffffffee, v84
	v_add_u32_e32 v7, 25, v81
	v_cndmask_b32_e64 v6, v6, v7, s[18:19]
	v_lshl_or_b32 v6, v6, 8, v88
	v_add_u32_e32 v231, s41, v6
	ds_read_b32 v121, v6
	ds_read_b32 v199, v231
	v_add_u32_e32 v6, 0xffffffed, v84
	v_add_u32_e32 v7, 26, v81
	v_cndmask_b32_e64 v6, v6, v7, s[18:19]
	v_lshl_or_b32 v6, v6, 8, v88
	v_add_u32_e32 v232, s41, v6
	ds_read_b32 v122, v6
	ds_read_b32 v200, v232
	v_add_u32_e32 v6, 0xffffffec, v84
	v_add_u32_e32 v7, 27, v81
	v_cndmask_b32_e64 v6, v6, v7, s[18:19]
	v_lshl_or_b32 v6, v6, 8, v88
	v_add_u32_e32 v233, s41, v6
	ds_read_b32 v123, v6
	ds_read_b32 v201, v233
	v_add_u32_e32 v6, 0xffffffeb, v84
	v_add_u32_e32 v7, 28, v81
	v_cndmask_b32_e64 v6, v6, v7, s[18:19]
	v_lshl_or_b32 v6, v6, 8, v88
	v_add_u32_e32 v234, s41, v6
	ds_read_b32 v124, v6
	ds_read_b32 v202, v234
	v_add_u32_e32 v6, 0xffffffea, v84
	v_add_u32_e32 v7, 29, v81
	v_cndmask_b32_e64 v6, v6, v7, s[18:19]
	v_lshl_or_b32 v6, v6, 8, v88
	v_add_u32_e32 v235, s41, v6
	ds_read_b32 v125, v6
	ds_read_b32 v203, v235
	v_add_u32_e32 v6, 0xffffffe9, v84
	v_add_u32_e32 v7, 30, v81
	v_cndmask_b32_e64 v6, v6, v7, s[18:19]
	v_lshl_or_b32 v6, v6, 8, v88
	v_add_u32_e32 v236, s41, v6
	ds_read_b32 v126, v6
	ds_read_b32 v204, v236
	v_add_u32_e32 v6, 0xffffffe8, v84
	v_add_u32_e32 v7, 31, v81
	v_cndmask_b32_e64 v6, v6, v7, s[18:19]
	v_lshl_or_b32 v6, v6, 8, v88
	v_add_u32_e32 v237, s41, v6
	ds_read_b32 v127, v6
	ds_read_b32 v205, v237
	s_waitcnt lgkmcnt(15)
	v_mul_f32_e32 v158, v157, v112
	v_fmac_f32_e32 v190, v189, v112
	v_mul_f32_e32 v159, v158, v113
	v_fmac_f32_e32 v191, v190, v113
	v_mul_f32_e32 v160, v159, v114
	v_fmac_f32_e32 v192, v191, v114
	v_mul_f32_e32 v161, v160, v115
	v_fmac_f32_e32 v193, v192, v115
	v_mul_f32_e32 v162, v161, v116
	v_fmac_f32_e32 v194, v193, v116
	v_mul_f32_e32 v163, v162, v117
	v_fmac_f32_e32 v195, v194, v117
	v_mul_f32_e32 v164, v163, v118
	v_fmac_f32_e32 v196, v195, v118
	v_mul_f32_e32 v165, v164, v119
	v_fmac_f32_e32 v197, v196, v119
	s_waitcnt lgkmcnt(0)
	v_mul_f32_e32 v166, v165, v120
	v_fmac_f32_e32 v198, v197, v120
	v_mul_f32_e32 v167, v166, v121
	v_fmac_f32_e32 v199, v198, v121
	v_mul_f32_e32 v168, v167, v122
	v_fmac_f32_e32 v200, v199, v122
	v_mul_f32_e32 v169, v168, v123
	v_fmac_f32_e32 v201, v200, v123
	v_mul_f32_e32 v170, v169, v124
	v_fmac_f32_e32 v202, v201, v124
	v_mul_f32_e32 v171, v170, v125
	v_fmac_f32_e32 v203, v202, v125
	v_mul_f32_e32 v172, v171, v126
	v_fmac_f32_e32 v204, v203, v126
	v_mul_f32_e32 v173, v172, v127
	v_fmac_f32_e32 v205, v204, v127
	v_mov_b32_e32 v2, v173
	v_mov_b32_e32 v3, v205
	ds_write_b64 v85, v[2:3]
	s_waitcnt lgkmcnt(0)
	s_barrier
	ds_read2st64_b64 v[2:5], v86 offset1:1
	ds_read2st64_b64 v[6:9], v86 offset0:2 offset1:3
	ds_read2st64_b64 v[14:17], v86 offset0:4 offset1:5
	s_lshl_b32 s22, s22, 8
	s_ashr_i32 s23, s22, 31
	s_waitcnt lgkmcnt(2)
	v_fma_f32 v10, v87, v2, v3
	v_cndmask_b32_e64 v10, v87, v10, s[2:3]
	v_fma_f32 v11, v10, v4, v5
	v_cndmask_b32_e64 v10, v10, v11, s[4:5]
	s_waitcnt lgkmcnt(1)
	v_fma_f32 v11, v10, v6, v7
	v_cndmask_b32_e64 v10, v10, v11, s[6:7]
	v_fma_f32 v11, v10, v8, v9
	v_cndmask_b32_e64 v78, v10, v11, s[8:9]
	ds_read2st64_b64 v[10:13], v86 offset0:6 offset1:7
	s_waitcnt lgkmcnt(1)
	v_fma_f32 v79, v78, v14, v15
	v_cndmask_b32_e64 v78, v78, v79, s[10:11]
	v_fma_f32 v79, v78, v16, v17
	v_cndmask_b32_e64 v78, v78, v79, s[12:13]
	s_waitcnt lgkmcnt(0)
	v_fma_f32 v79, v78, v10, v11
	s_add_u32 s22, s46, s22
	v_cndmask_b32_e64 v78, v78, v79, s[14:15]
	s_addc_u32 s23, s43, s23
	v_fma_f32 v79, v78, v12, v13
	s_lshl_b64 s[22:23], s[22:23], 12
	v_cndmask_b32_e64 v89, v78, v79, s[16:17]
	v_lshl_add_u64 v[78:79], v[48:49], 0, s[22:23]
	s_mov_b32 s22, 0
	v_mov_b32_e32 v90, v84
; __device__ __forceinline__ bf16_t f2bf(float x) { return (bf16_t)(cvt_pk_bf16(x, 0.f) & 0xffffu); }
; __global__ void __launch_bounds__(NTHR, 2) fwd(Args args) {
;     ...
;                         float st = hcar, pt = 1.f, ht = 0.f;
; #pragma unroll
;                         for (int k = 0; k < 8; ++k) { const float sp_ = seg[(k * 64 + ch) * 2], sh_ = seg[(k * 64 + ch) * 2 + 1]; if (k < sg) st = sp_ * st + sh_; ht = sp_ * ht + sh_; pt *= sp_; }
;                         const size_t ob = ((size_t)dir * R + pm * 256) * D + ch0 + ch;
; #pragma unroll 8
;                         for (int i = 0; i < 32; ++i) { const int r = dir == 0 ? 32 * sg + i : 255 - (32 * sg + i); HF[ob + (size_t)r * D] = f2bf(Bl[r * 64 + ch] + Al[r * 64 + ch] * st); }
;                         hcar = pt * hcar + ht;
;                         __syncthreads();
.LBB0_1442:
	v_fmac_f32_e32 v174, v89, v142
	v_fmac_f32_e32 v175, v89, v143
	v_fmac_f32_e32 v176, v89, v144
	v_fmac_f32_e32 v177, v89, v145
	v_fmac_f32_e32 v178, v89, v146
	v_fmac_f32_e32 v179, v89, v147
	v_fmac_f32_e32 v180, v89, v148
	v_fmac_f32_e32 v181, v89, v149
	ds_write_b32 v206, v174
	ds_write_b32 v207, v175
	ds_write_b32 v208, v176
	ds_write_b32 v209, v177
	ds_write_b32 v210, v178
	ds_write_b32 v211, v179
	ds_write_b32 v212, v180
	ds_write_b32 v213, v181
	v_fmac_f32_e32 v182, v89, v150
	v_fmac_f32_e32 v183, v89, v151
	v_fmac_f32_e32 v184, v89, v152
	v_fmac_f32_e32 v185, v89, v153
	v_fmac_f32_e32 v186, v89, v154
	v_fmac_f32_e32 v187, v89, v155
	v_fmac_f32_e32 v188, v89, v156
	v_fmac_f32_e32 v189, v89, v157
	ds_write_b32 v214, v182
	ds_write_b32 v215, v183
	ds_write_b32 v216, v184
	ds_write_b32 v217, v185
	ds_write_b32 v218, v186
	ds_write_b32 v219, v187
	ds_write_b32 v220, v188
	ds_write_b32 v221, v189
	v_fmac_f32_e32 v190, v89, v158
	v_fmac_f32_e32 v191, v89, v159
	v_fmac_f32_e32 v192, v89, v160
	v_fmac_f32_e32 v193, v89, v161
	v_fmac_f32_e32 v194, v89, v162
	v_fmac_f32_e32 v195, v89, v163
	v_fmac_f32_e32 v196, v89, v164
	v_fmac_f32_e32 v197, v89, v165
	ds_write_b32 v222, v190
	ds_write_b32 v223, v191
	ds_write_b32 v224, v192
	ds_write_b32 v225, v193
	ds_write_b32 v226, v194
	ds_write_b32 v227, v195
	ds_write_b32 v228, v196
	ds_write_b32 v229, v197
	v_fmac_f32_e32 v198, v89, v166
	v_fmac_f32_e32 v199, v89, v167
	v_fmac_f32_e32 v200, v89, v168
	v_fmac_f32_e32 v201, v89, v169
	v_fmac_f32_e32 v202, v89, v170
	v_fmac_f32_e32 v203, v89, v171
	v_fmac_f32_e32 v204, v89, v172
	v_fmac_f32_e32 v205, v89, v173
	ds_write_b32 v230, v198
	ds_write_b32 v231, v199
	ds_write_b32 v232, v200
	ds_write_b32 v233, v201
	ds_write_b32 v234, v202
	ds_write_b32 v235, v203
	ds_write_b32 v236, v204
	ds_write_b32 v237, v205
	v_fma_f32 v3, 0, v2, v3
	v_fma_f32 v3, v3, v4, v5
	v_mul_f32_e32 v2, v2, v4
	v_fma_f32 v3, v3, v6, v7
	v_mul_f32_e32 v2, v2, v6
	v_fma_f32 v3, v3, v8, v9
	v_mul_f32_e32 v2, v2, v8
	v_fma_f32 v3, v3, v14, v15
	v_mul_f32_e32 v2, v2, v14
	v_fma_f32 v3, v3, v16, v17
	v_mul_f32_e32 v2, v2, v16
	v_fma_f32 v3, v3, v10, v11
	v_mul_f32_e32 v2, v2, v10
	v_mul_f32_e32 v2, v2, v12
	v_fmac_f32_e32 v13, v3, v12
	v_fmac_f32_e32 v13, v87, v2
	s_add_i32 s22, s24, 1
	s_not_b32 s23, s24
	s_cmp_eq_u32 s22, 9
	v_mov_b32_e32 v87, v13
	s_mov_b32 s24, s22
	s_waitcnt lgkmcnt(0)
	s_barrier
	v_lshrrev_b32_e32 v96, 2, v81
	v_lshrrev_b32_e32 v97, 3, v80
	v_add_u32_e32 v96, v96, v97
	v_and_b32_e32 v97, 7, v80
	v_lshlrev_b32_e32 v98, 8, v96
	v_lshl_add_u32 v98, v97, 5, v98
	v_add_u32_e32 v98, s41, v98
	ds_read_b128 v[100:103], v98
	ds_read_b128 v[104:107], v98 offset:16
	ds_read_b128 v[108:111], v98 offset:16384
	ds_read_b128 v[112:115], v98 offset:16400
	ds_read_b128 v[116:119], v98 offset:32768
	ds_read_b128 v[120:123], v98 offset:32784
	ds_read_b128 v[124:127], v98 offset:49152
	ds_read_b128 v[128:131], v98 offset:49168
	v_lshlrev_b32_e32 v99, 1, v80
	v_mov_b32_e32 v133, 0
	v_lshlrev_b32_e32 v132, 12, v96
	v_lshl_add_u32 v132, v97, 4, v132
	v_sub_u32_e32 v132, v132, v99
	v_ashrrev_i32_e32 v133, 31, v132
	v_lshl_add_u64 v[134:135], v[78:79], 0, v[132:133]
	s_mov_b64 s[98:99], 0x40000
	v_lshl_add_u64 v[136:137], v[134:135], 0, s[98:99]
	v_lshl_add_u64 v[138:139], v[136:137], 0, s[98:99]
	v_lshl_add_u64 v[140:141], v[138:139], 0, s[98:99]
	s_waitcnt lgkmcnt(6)
	v_cvt_pk_bf16_f32 v100, v100, v101
	v_cvt_pk_bf16_f32 v101, v102, v103
	v_cvt_pk_bf16_f32 v102, v104, v105
	v_cvt_pk_bf16_f32 v103, v106, v107
	global_store_dwordx4 v[134:135], v[100:103], off
	s_waitcnt lgkmcnt(4)
	v_cvt_pk_bf16_f32 v108, v108, v109
	v_cvt_pk_bf16_f32 v109, v110, v111
	v_cvt_pk_bf16_f32 v110, v112, v113
	v_cvt_pk_bf16_f32 v111, v114, v115
	global_store_dwordx4 v[136:137], v[108:111], off
	s_waitcnt lgkmcnt(2)
	v_cvt_pk_bf16_f32 v116, v116, v117
	v_cvt_pk_bf16_f32 v117, v118, v119
	v_cvt_pk_bf16_f32 v118, v120, v121
	v_cvt_pk_bf16_f32 v119, v122, v123
	global_store_dwordx4 v[138:139], v[116:119], off
	s_waitcnt lgkmcnt(0)
	v_cvt_pk_bf16_f32 v124, v124, v125
	v_cvt_pk_bf16_f32 v125, v126, v127
	v_cvt_pk_bf16_f32 v126, v128, v129
	v_cvt_pk_bf16_f32 v127, v130, v131
	global_store_dwordx4 v[140:141], v[124:127], off
	s_barrier
	s_cmp_eq_u32 s24, 9
	s_cbranch_scc0 .LBB0_1432
	s_add_i32 s33, s33, s40
	s_cmpk_gt_i32 s33, 0xff
	s_cbranch_scc0 .LBB0_1431
